# MoBA: gathered-Q register copy waits vmcnt(4) instead of vmcnt(0) (does not drain the step's K/V prefetch)
# baseline (speedup 1.0000x reference)
; template <bool MOBA>
; __device__ __forceinline__ void attn_unit(unsigned char* lds, LAS unsigned char* lds3, const Params& p, int b, int h, int qb) {
;     ...
;         if (MOBA && tl < 0) {
;             const int j = t >> 2; const int nj = __builtin_amdgcn_readfirstlane(njs[j]);
;             active = (32 * w < nj);
;             if (active && (t & 3) == 3) {
; #pragma unroll
;                 for (int jb = 0; jb < 2; ++jb) { const int slot = 32 * w + 16 * jb + fr; qv[jb] = slot < nj; const int q = qv[jb] ? (int)listq[j * 256 + slot] : 0; qpl[jb] = q; mrc[jb] = mrefs[q];
; #pragma unroll
;                     for (int ks = 0; ks < 2; ++ks) qf[jb][ks] = qn[jb][ks]; }
.LBB0_463:
	s_add_i32 s28, s34, s27
	s_add_i32 s4, s28, 1
	s_add_i32 s5, s27, 1
	s_cmp_le_i32 s5, s21
	s_cselect_b64 s[6:7], -1, 0
	s_cmp_gt_i32 s5, -1
	s_cbranch_scc1 .LBB0_478
	s_and_b32 s5, s4, -4
	s_add_i32 s29, s5, 0
	s_add_i32 s29, s29, 0x14d00
	v_mov_b32_e32 v1, s29
	ds_read_b32 v1, v1
	s_ashr_i32 s5, s4, 2
	s_waitcnt lgkmcnt(0)
	v_readfirstlane_b32 s18, v1
	s_cmp_lt_i32 s41, s18
	s_cselect_b64 s[6:7], -1, 0
	s_and_b32 s16, s4, 3
	s_cmp_eq_u32 s16, 3
	s_cselect_b64 s[16:17], -1, 0
	s_and_b64 s[30:31], s[16:17], s[6:7]
	s_andn2_b64 vcc, exec, s[30:31]
	s_cbranch_vccnz .LBB0_470
	s_lshl_b32 s10, s5, 8
	s_add_i32 s10, s10, 0
	s_add_i32 s12, s10, 0x13880
	v_cmp_gt_i32_e64 s[10:11], s18, v120
	v_mov_b32_e32 v125, 0
	v_add_u32_e32 v1, s12, v120
	v_mov_b32_e32 v124, 0
	s_and_saveexec_b64 s[12:13], s[10:11]
	ds_read_u8 v124, v1
	s_or_b64 exec, exec, s[12:13]
	s_waitcnt lgkmcnt(0)
	v_lshl_add_u32 v2, v124, 2, 0
	v_add_u32_e32 v2, 0x14880, v2
	ds_read_b32 v122, v2
	v_cmp_gt_i32_e64 s[12:13], s18, v121
	s_and_saveexec_b64 s[18:19], s[12:13]
	ds_read_u8 v125, v1 offset:16
	s_or_b64 exec, exec, s[18:19]
	s_waitcnt lgkmcnt(0)
	v_lshl_add_u32 v1, v125, 2, 0
	v_add_u32_e32 v1, 0x14880, v1
	ds_read_b32 v123, v1
	s_waitcnt vmcnt(4)
	v_mov_b64_e32 v[12:13], v[48:49]
	v_mov_b64_e32 v[16:17], v[44:45]
	v_mov_b64_e32 v[4:5], v[40:41]
	v_mov_b64_e32 v[8:9], v[36:37]
	v_mov_b64_e32 v[14:15], v[50:51]
	v_mov_b64_e32 v[18:19], v[46:47]
	v_mov_b64_e32 v[6:7], v[42:43]
	v_mov_b64_e32 v[10:11], v[38:39]
